# speedup vs baseline: 1.0257x; 1.0007x over previous
; __device__ __forceinline__ float bflo(unsigned w) { return __uint_as_float(w << 16); }
; __device__ __forceinline__ void norm_rows_b(const bf16_t* hb, int r_begin, int nrows, int stride, int second_off, const float* modl, int shoff, int scoff, bf16_t* xl) {
;     ...
;     for (int r = r_begin; r < nrows; r += stride) {
;         const int r1 = r + second_off; const bool two = r1 < nrows;
;         u32x4 w[2][2]; float s[2];
; #pragma unroll
;         for (int q = 0; q < 2; ++q) { const bf16_t* xr = hb + (size_t)(q ? (two ? r1 : r) : r) * DM + 8 * lane; w[q][0] = *(const u32x4*)(xr); w[q][1] = *(const u32x4*)(xr + 512); }
;         float v[2][16];
; #pragma unroll
;         for (int q = 0; q < 2; ++q) { float a = 0.f;
; #pragma unroll
;             for (int h = 0; h < 2; ++h)
; #pragma unroll
;                 for (int e = 0; e < 4; ++e) { const float lo = bflo(w[q][h][e]), hi = bfhi(w[q][h][e]); v[q][8 * h + 2 * e] = lo; v[q][8 * h + 2 * e + 1] = hi; a += lo * lo + hi * hi; }
;             s[q] = a; }
; #pragma unroll
;         for (int o = 32; o > 0; o >>= 1) { s[0] += __shfl_xor(s[0], o); s[1] += __shfl_xor(s[1], o); }
; #pragma unroll
;         for (int q = 0; q < 2; ++q) { if (q == 1 && !two) break; const int rr = q ? r1 : r; const int cond = rr < MLAT ? (rr >> 13) : 8; const float* mp = modl + cond * 6144;
;             const float rstd = rsqrtf(s[q] * (1.0f / DM) + EPS);
; #pragma unroll
;             for (int h = 0; h < 2; ++h) { const int col = 8 * lane + 512 * h; const f32x4 sc0 = *(const f32x4*)(mp + scoff + col), sc1 = *(const f32x4*)(mp + scoff + col + 4), sh0 = *(const f32x4*)(mp + shoff + col), sh1 = *(const f32x4*)(mp + shoff + col + 4);
;                 u32x4 o;
;                 o.x = cvt_pk_bf16(v[q][8 * h + 0] * rstd * (sc0[0] + 1.0f) + sh0[0], v[q][8 * h + 1] * rstd * (sc0[1] + 1.0f) + sh0[1]);
;                 o.y = cvt_pk_bf16(v[q][8 * h + 2] * rstd * (sc0[2] + 1.0f) + sh0[2], v[q][8 * h + 3] * rstd * (sc0[3] + 1.0f) + sh0[3]);
;                 o.z = cvt_pk_bf16(v[q][8 * h + 4] * rstd * (sc1[0] + 1.0f) + sh1[0], v[q][8 * h + 5] * rstd * (sc1[1] + 1.0f) + sh1[1]);
;                 o.w = cvt_pk_bf16(v[q][8 * h + 6] * rstd * (sc1[2] + 1.0f) + sh1[2], v[q][8 * h + 7] * rstd * (sc1[3] + 1.0f) + sh1[3]);
;                 *(u32x4*)(xl + (size_t)rr * DM + col) = o; } }
.LBB0_335:
	v_ashrrev_i32_e32 v13, 31, v12
	v_lshlrev_b64 v[30:31], 11, v[12:13]
	s_waitcnt lgkmcnt(0)
	v_lshl_add_u64 v[10:11], v[2:3], 0, v[30:31]
	global_load_dwordx4 v[22:25], v[10:11], off
	global_load_dwordx4 v[26:29], v[10:11], off offset:1024
	v_min_i32_e32 v7, 0x10000, v12
	v_add_u32_e32 v10, s42, v12
	v_ashrrev_i32_e32 v7, 13, v7
	v_cmp_gt_i32_e32 vcc, s12, v10
	v_mul_i32_i24_e32 v32, 0x1800, v7
	v_ashrrev_i32_e32 v33, 31, v32
	v_cndmask_b32_e32 v12, v12, v10, vcc
	v_ashrrev_i32_e32 v13, 31, v12
	v_lshl_add_u64 v[48:49], v[32:33], 2, s[54:55]
	v_lshlrev_b64 v[12:13], 11, v[12:13]
	v_lshl_add_u64 v[56:57], v[48:49], 0, s[8:9]
	v_lshl_add_u64 v[12:13], v[2:3], 0, v[12:13]
	v_lshl_add_u64 v[40:41], v[56:57], 0, v[0:1]
	global_load_dwordx4 v[32:35], v[12:13], off
	global_load_dwordx4 v[80:83], v[40:41], off offset:2064
	global_load_dwordx4 v[84:87], v[40:41], off offset:2048
	global_load_dwordx4 v[36:39], v[40:41], off
	s_nop 0
	global_load_dwordx4 v[40:43], v[40:41], off offset:16
	s_nop 0
	global_load_dwordx4 v[44:47], v[12:13], off offset:1024
	v_lshl_add_u64 v[12:13], v[48:49], 0, s[10:11]
	v_lshl_add_u64 v[52:53], v[12:13], 0, v[0:1]
	global_load_dwordx4 v[88:91], v[52:53], off offset:2064
	global_load_dwordx4 v[92:95], v[52:53], off offset:2048
	global_load_dwordx4 v[48:51], v[52:53], off offset:16
	s_nop 0
	global_load_dwordx4 v[52:55], v[52:53], off
	v_lshl_add_u64 v[66:67], v[4:5], 0, v[30:31]
	v_lshl_add_u64 v[12:13], v[12:13], 0, v[8:9]
	v_min_i32_e32 v147, 0x10000, v10
	v_ashrrev_i32_e32 v147, 13, v147
	v_mul_i32_i24_e32 v148, 0x1800, v147
	v_ashrrev_i32_e32 v149, 31, v148
	v_lshl_add_u64 v[96:97], v[148:149], 2, s[54:55]
	v_lshl_add_u64 v[98:99], v[96:97], 0, s[8:9]
	v_lshl_add_u64 v[100:101], v[98:99], 0, v[0:1]
	v_lshl_add_u64 v[102:103], v[96:97], 0, s[10:11]
	global_load_dwordx4 v[104:107], v[100:101], off offset:2048
	global_load_dwordx4 v[108:111], v[100:101], off offset:2064
	global_load_dwordx4 v[112:115], v[100:101], off
	global_load_dwordx4 v[116:119], v[100:101], off offset:16
	v_lshl_add_u64 v[120:121], v[102:103], 0, v[0:1]
	global_load_dwordx4 v[122:125], v[120:121], off offset:2048
	global_load_dwordx4 v[126:129], v[120:121], off offset:2064
	global_load_dwordx4 v[130:133], v[120:121], off
	global_load_dwordx4 v[134:137], v[120:121], off offset:16
	s_waitcnt vmcnt(19)
	v_and_b32_e32 v11, 0xffff0000, v22
	v_and_b32_e32 v69, 0xffff0000, v23
	v_lshlrev_b32_e32 v7, 16, v22
	v_lshlrev_b32_e32 v68, 16, v23
	v_and_b32_e32 v71, 0xffff0000, v24
	s_waitcnt vmcnt(18)
	v_lshlrev_b32_e32 v58, 16, v26
	v_and_b32_e32 v60, 0xffff0000, v26
	v_mul_f32_e32 v21, v11, v11
	v_mul_f32_e32 v26, v69, v69
	v_lshlrev_b32_e32 v70, 16, v24
	v_and_b32_e32 v73, 0xffff0000, v25
	v_lshlrev_b32_e32 v59, 16, v27
	v_and_b32_e32 v61, 0xffff0000, v27
	v_mul_f32_e32 v27, v71, v71
	v_fmac_f32_e32 v21, v7, v7
	v_fmac_f32_e32 v26, v68, v68
	v_lshlrev_b32_e32 v72, 16, v25
	v_lshlrev_b32_e32 v62, 16, v28
	v_and_b32_e32 v64, 0xffff0000, v28
	v_mul_f32_e32 v28, v73, v73
	v_fmac_f32_e32 v27, v70, v70
	v_add_f32_e32 v21, v21, v26
	v_pk_mul_f32 v[22:23], v[60:61], v[60:61]
	v_fmac_f32_e32 v28, v72, v72
	v_add_f32_e32 v21, v27, v21
	v_and_b32_e32 v65, 0xffff0000, v29
	v_pk_fma_f32 v[22:23], v[58:59], v[58:59], v[22:23]
	v_add_f32_e32 v21, v28, v21
	v_lshlrev_b32_e32 v63, 16, v29
	v_pk_mul_f32 v[24:25], v[64:65], v[64:65]
	v_add_f32_e32 v21, v22, v21
	v_pk_fma_f32 v[24:25], v[62:63], v[62:63], v[24:25]
	v_add_f32_e32 v21, v23, v21
	v_add_f32_e32 v21, v24, v21
	v_add_f32_e32 v21, v25, v21
	ds_bpermute_b32 v22, v14, v21
	s_waitcnt vmcnt(14)
	v_add_f32_e32 v25, 1.0, v37
	v_lshl_add_u64 v[26:27], v[56:57], 0, v[8:9]
	v_add_f32_e32 v24, 1.0, v36
	v_add_f32_e32 v28, 1.0, v38
	s_waitcnt lgkmcnt(0)
	v_add_f32_e32 v21, v21, v22
	ds_bpermute_b32 v22, v15, v21
	s_waitcnt vmcnt(13)
	v_add_f32_e32 v30, 1.0, v40
	v_add_f32_e32 v29, 1.0, v39
	v_add_f32_e32 v31, 1.0, v42
	v_add_f32_e32 v36, 1.0, v43
	s_waitcnt lgkmcnt(0)
	v_add_f32_e32 v21, v21, v22
	ds_bpermute_b32 v22, v16, v21
	s_waitcnt lgkmcnt(0)
	v_add_f32_e32 v21, v21, v22
	ds_bpermute_b32 v22, v17, v21
	s_waitcnt lgkmcnt(0)
	v_add_f32_e32 v22, v21, v22
	ds_bpermute_b32 v23, v18, v22
	v_lshlrev_b32_e32 v21, 16, v32
	s_waitcnt lgkmcnt(0)
	v_add_f32_e32 v22, v22, v23
	ds_bpermute_b32 v23, v19, v22
	s_waitcnt lgkmcnt(0)
	v_add_f32_e32 v22, v22, v23
	v_fmamk_f32 v22, v22, 0x3a800000, v20
	v_mul_f32_e32 v23, 0x4b800000, v22
	v_cmp_gt_f32_e64 s[6:7], s13, v22
	s_nop 1
	v_cndmask_b32_e64 v22, v22, v23, s[6:7]
	v_rsq_f32_e32 v22, v22
	v_add_f32_e32 v23, 1.0, v41
	v_mul_f32_e32 v37, 0x45800000, v22
	v_cndmask_b32_e64 v56, v22, v37, s[6:7]
	v_mul_f32_e32 v7, v56, v7
	v_mul_f32_e32 v11, v56, v11
	v_mul_f32_e32 v22, v56, v68
	v_mul_f32_e32 v38, v56, v70
	v_mul_f32_e32 v37, v56, v69
	v_mul_f32_e32 v39, v56, v71
	v_mul_f32_e32 v40, v56, v72
	v_mul_f32_e32 v41, v56, v73
	s_waitcnt vmcnt(8)
; __device__ __forceinline__ float bflo(unsigned w) { return __uint_as_float(w << 16); }
; __device__ __forceinline__ void norm_rows_b(const bf16_t* hb, int r_begin, int nrows, int stride, int second_off, const float* modl, int shoff, int scoff, bf16_t* xl) {
;     ...
;     for (int r = r_begin; r < nrows; r += stride) {
;         const int r1 = r + second_off; const bool two = r1 < nrows;
;         u32x4 w[2][2]; float s[2];
; #pragma unroll
;         for (int q = 0; q < 2; ++q) { const bf16_t* xr = hb + (size_t)(q ? (two ? r1 : r) : r) * DM + 8 * lane; w[q][0] = *(const u32x4*)(xr); w[q][1] = *(const u32x4*)(xr + 512); }
;         float v[2][16];
; #pragma unroll
;         for (int q = 0; q < 2; ++q) { float a = 0.f;
; #pragma unroll
;             for (int h = 0; h < 2; ++h)
; #pragma unroll
;                 for (int e = 0; e < 4; ++e) { const float lo = bflo(w[q][h][e]), hi = bfhi(w[q][h][e]); v[q][8 * h + 2 * e] = lo; v[q][8 * h + 2 * e + 1] = hi; a += lo * lo + hi * hi; }
;             s[q] = a; }
; #pragma unroll
;         for (int o = 32; o > 0; o >>= 1) { s[0] += __shfl_xor(s[0], o); s[1] += __shfl_xor(s[1], o); }
; #pragma unroll
;         for (int q = 0; q < 2; ++q) { if (q == 1 && !two) break; const int rr = q ? r1 : r; const int cond = rr < MLAT ? (rr >> 13) : 8; const float* mp = modl + cond * 6144;
;             const float rstd = rsqrtf(s[q] * (1.0f / DM) + EPS);
; #pragma unroll
;             for (int h = 0; h < 2; ++h) { const int col = 8 * lane + 512 * h; const f32x4 sc0 = *(const f32x4*)(mp + scoff + col), sc1 = *(const f32x4*)(mp + scoff + col + 4), sh0 = *(const f32x4*)(mp + shoff + col), sh1 = *(const f32x4*)(mp + shoff + col + 4);
;                 u32x4 o;
;                 o.x = cvt_pk_bf16(v[q][8 * h + 0] * rstd * (sc0[0] + 1.0f) + sh0[0], v[q][8 * h + 1] * rstd * (sc0[1] + 1.0f) + sh0[1]);
;                 o.y = cvt_pk_bf16(v[q][8 * h + 2] * rstd * (sc0[2] + 1.0f) + sh0[2], v[q][8 * h + 3] * rstd * (sc0[3] + 1.0f) + sh0[3]);
;                 o.z = cvt_pk_bf16(v[q][8 * h + 4] * rstd * (sc1[0] + 1.0f) + sh1[0], v[q][8 * h + 5] * rstd * (sc1[1] + 1.0f) + sh1[1]);
;                 o.w = cvt_pk_bf16(v[q][8 * h + 6] * rstd * (sc1[2] + 1.0f) + sh1[2], v[q][8 * h + 7] * rstd * (sc1[3] + 1.0f) + sh1[3]);
;                 *(u32x4*)(xl + (size_t)rr * DM + col) = o; } }
	v_fma_f32 v7, v24, v7, v52
	v_fma_f32 v11, v25, v11, v53
	v_fma_f32 v24, v28, v22, v54
	v_fma_f32 v25, v30, v38, v48
	v_fmac_f32_e32 v55, v29, v37
	v_fma_f32 v28, v23, v39, v49
	v_fma_f32 v29, v31, v40, v50
	v_fmac_f32_e32 v51, v36, v41
	v_cvt_pk_bf16_f32 v22, v7, v11
	v_cvt_pk_bf16_f32 v23, v24, v55
	v_cvt_pk_bf16_f32 v24, v25, v28
	v_cvt_pk_bf16_f32 v25, v29, v51
	global_store_dwordx4 v[66:67], v[22:25], off
	v_and_b32_e32 v28, 0xffff0000, v32
	v_and_b32_e32 v30, 0xffff0000, v33
	v_lshlrev_b32_e32 v29, 16, v33
	v_and_b32_e32 v32, 0xffff0000, v34
	v_mul_f32_e32 v7, v28, v28
	v_mul_f32_e32 v11, v30, v30
	v_lshlrev_b32_e32 v31, 16, v34
	v_lshlrev_b32_e32 v33, 16, v35
	v_and_b32_e32 v34, 0xffff0000, v35
	v_mul_f32_e32 v35, v32, v32
	v_fmac_f32_e32 v7, v21, v21
	v_fmac_f32_e32 v11, v29, v29
	v_lshlrev_b32_e32 v27, 16, v44
	v_and_b32_e32 v26, 0xffff0000, v44
	v_mul_f32_e32 v44, v34, v34
	v_fmac_f32_e32 v35, v31, v31
	v_add_f32_e32 v7, v7, v11
	v_lshlrev_b32_e32 v25, 16, v45
	v_and_b32_e32 v24, 0xffff0000, v45
	v_mul_f32_e32 v45, v26, v26
	v_fmac_f32_e32 v44, v33, v33
	v_add_f32_e32 v7, v35, v7
	v_lshlrev_b32_e32 v23, 16, v46
	v_and_b32_e32 v22, 0xffff0000, v46
	v_mul_f32_e32 v46, v24, v24
	v_fmac_f32_e32 v45, v27, v27
	v_add_f32_e32 v7, v44, v7
	v_lshlrev_b32_e32 v13, 16, v47
	v_and_b32_e32 v12, 0xffff0000, v47
	v_mul_f32_e32 v47, v22, v22
	v_fmac_f32_e32 v46, v25, v25
	v_add_f32_e32 v7, v45, v7
	v_mul_f32_e32 v57, v12, v12
	v_fmac_f32_e32 v47, v23, v23
	v_add_f32_e32 v7, v46, v7
	v_fmac_f32_e32 v57, v13, v13
	v_add_f32_e32 v7, v47, v7
	v_add_f32_e32 v7, v57, v7
	ds_bpermute_b32 v11, v14, v7
	v_mul_f32_e32 v35, v56, v58
	v_mul_f32_e32 v44, v56, v60
	v_mul_f32_e32 v45, v56, v59
	v_mul_f32_e32 v46, v56, v61
	s_waitcnt lgkmcnt(0)
	v_add_f32_e32 v7, v7, v11
	ds_bpermute_b32 v11, v15, v7
	v_mul_f32_e32 v47, v56, v62
	v_mul_f32_e32 v57, v56, v64
	v_mul_f32_e32 v58, v56, v63
	v_mul_f32_e32 v56, v56, v65
	s_waitcnt lgkmcnt(0)
	v_add_f32_e32 v7, v7, v11
	ds_bpermute_b32 v11, v16, v7
	s_waitcnt lgkmcnt(0)
	v_add_f32_e32 v7, v7, v11
	ds_bpermute_b32 v11, v17, v7
	s_waitcnt lgkmcnt(0)
	v_add_f32_e32 v7, v7, v11
	ds_bpermute_b32 v11, v18, v7
	s_waitcnt lgkmcnt(0)
	v_add_f32_e32 v7, v7, v11
	ds_bpermute_b32 v11, v19, v7
	s_waitcnt vmcnt(17)
	v_add_f32_e32 v36, 1.0, v80
	s_waitcnt vmcnt(16)
	v_add_f32_e32 v40, 1.0, v84
	v_add_f32_e32 v41, 1.0, v85
	v_add_f32_e32 v42, 1.0, v86
	v_add_f32_e32 v43, 1.0, v87
	v_add_f32_e32 v37, 1.0, v81
	v_add_f32_e32 v38, 1.0, v82
	v_add_f32_e32 v39, 1.0, v83
	s_waitcnt vmcnt(11)
	v_fma_f32 v35, v40, v35, v92
	v_fma_f32 v40, v41, v44, v93
	v_fma_f32 v41, v42, v45, v94
	v_fma_f32 v55, v43, v46, v95
	v_fma_f32 v42, v47, v36, v88
	v_fma_f32 v43, v57, v37, v89
	v_fma_f32 v44, v58, v38, v90
	v_fma_f32 v51, v56, v39, v91
	v_cvt_pk_bf16_f32 v36, v35, v40
	v_cvt_pk_bf16_f32 v37, v41, v55
	v_cvt_pk_bf16_f32 v38, v42, v43
	v_cvt_pk_bf16_f32 v39, v44, v51
	global_store_dwordx4 v[66:67], v[36:39], off offset:1024
	s_and_saveexec_b64 s[6:7], vcc
	s_cbranch_execz .LBB0_334
	s_waitcnt lgkmcnt(0)
	v_add_f32_e32 v35, v7, v11
	v_fmamk_f32 v35, v35, 0x3a800000, v20
	v_mul_f32_e32 v56, 0x4b800000, v35
	v_cmp_gt_f32_e32 vcc, s13, v35
	v_ashrrev_i32_e32 v11, 31, v10
	v_mov_b32_e32 v7, v1
	v_cndmask_b32_e32 v35, v35, v56, vcc
	v_rsq_f32_e32 v35, v35
	v_lshlrev_b64 v[56:57], 11, v[10:11]
	v_lshl_add_u64 v[56:57], v[4:5], 0, v[56:57]
	v_lshl_add_u64 v[52:53], v[98:99], 0, v[6:7]
	v_mul_f32_e32 v11, 0x45800000, v35
	v_cndmask_b32_e32 v11, v35, v11, vcc
	v_mul_f32_e32 v28, v11, v28
	v_mul_f32_e32 v29, v11, v29
	v_mul_f32_e32 v30, v11, v30
	v_mul_f32_e32 v31, v11, v31
	v_mul_f32_e32 v32, v11, v32
	v_mul_f32_e32 v21, v11, v21
	v_mul_f32_e32 v33, v11, v33
	v_mul_f32_e32 v34, v11, v34
	v_mul_f32_e32 v25, v11, v25
	v_mul_f32_e32 v24, v11, v24
	v_mul_f32_e32 v23, v11, v23
	v_mul_f32_e32 v22, v11, v22
	v_mul_f32_e32 v13, v11, v13
	s_waitcnt vmcnt(7)
	v_add_f32_e32 v35, 1.0, v112
	v_add_f32_e32 v36, 1.0, v113
	v_add_f32_e32 v37, 1.0, v114
	v_add_f32_e32 v38, 1.0, v115
	s_waitcnt vmcnt(6)
	v_add_f32_e32 v39, 1.0, v116
	v_add_f32_e32 v40, 1.0, v117
	v_add_f32_e32 v41, 1.0, v118
	v_add_f32_e32 v42, 1.0, v119
	s_waitcnt vmcnt(3)
	v_fma_f32 v28, v28, v36, v131
	v_fma_f32 v29, v29, v37, v132
	v_fma_f32 v47, v30, v38, v133
	s_waitcnt vmcnt(2)
	v_fma_f32 v30, v31, v39, v134
	v_fma_f32 v31, v32, v40, v135
	v_fma_f32 v21, v21, v35, v130
	v_fma_f32 v32, v33, v41, v136
	v_fma_f32 v51, v34, v42, v137
	v_cvt_pk_bf16_f32 v28, v21, v28
	v_cvt_pk_bf16_f32 v29, v29, v47
	v_cvt_pk_bf16_f32 v30, v30, v31
	v_cvt_pk_bf16_f32 v31, v32, v51
	global_store_dwordx4 v[56:57], v[28:31], off
	s_nop 0
	v_lshl_add_u64 v[40:41], v[102:103], 0, v[6:7]
	s_nop 0
	v_mul_f32_e32 v7, v11, v27
	v_mul_f32_e32 v21, v11, v26
	v_mul_f32_e32 v11, v11, v12
	s_waitcnt vmcnt(10)
	v_add_f32_e32 v12, 1.0, v104
	v_add_f32_e32 v26, 1.0, v105
	v_add_f32_e32 v27, 1.0, v106
	v_add_f32_e32 v28, 1.0, v107
	s_waitcnt vmcnt(9)
	v_add_f32_e32 v29, 1.0, v108
	v_add_f32_e32 v30, 1.0, v109
	v_add_f32_e32 v31, 1.0, v110
	v_add_f32_e32 v32, 1.0, v111
	s_waitcnt vmcnt(6)
	v_fma_f32 v7, v7, v12, v122
	v_fma_f32 v12, v21, v26, v123
	v_fma_f32 v21, v25, v27, v124
	v_fma_f32 v39, v24, v28, v125
	s_waitcnt vmcnt(5)
	v_fma_f32 v24, v23, v29, v126
	v_fma_f32 v25, v22, v30, v127
	v_fma_f32 v13, v13, v31, v128
	v_fma_f32 v43, v11, v32, v129
	v_cvt_pk_bf16_f32 v22, v7, v12
	v_cvt_pk_bf16_f32 v23, v21, v39
	v_cvt_pk_bf16_f32 v24, v24, v25
	v_cvt_pk_bf16_f32 v25, v13, v43
	global_store_dwordx4 v[56:57], v[22:25], off offset:1024
	s_branch .LBB0_334

; __device__ __forceinline__ float bflo(unsigned w) { return __uint_as_float(w << 16); }
; __device__ __forceinline__ float bfhi(unsigned w) { return __uint_as_float(w & 0xffff0000u); }
; __device__ __forceinline__ void norm_rows_b(const bf16_t* hb, int r_begin, int nrows, int stride, int second_off, const float* modl, int shoff, int scoff, bf16_t* xl) {
;     ...
;     for (int r = r_begin; r < nrows; r += stride) {
;         const int r1 = r + second_off; const bool two = r1 < nrows;
;         u32x4 w[2][2]; float s[2];
; #pragma unroll
;         for (int q = 0; q < 2; ++q) { const bf16_t* xr = hb + (size_t)(q ? (two ? r1 : r) : r) * DM + 8 * lane; w[q][0] = *(const u32x4*)(xr); w[q][1] = *(const u32x4*)(xr + 512); }
;         float v[2][16];
; #pragma unroll
;         for (int q = 0; q < 2; ++q) { float a = 0.f;
; #pragma unroll
;             for (int h = 0; h < 2; ++h)
; #pragma unroll
;                 for (int e = 0; e < 4; ++e) { const float lo = bflo(w[q][h][e]), hi = bfhi(w[q][h][e]); v[q][8 * h + 2 * e] = lo; v[q][8 * h + 2 * e + 1] = hi; a += lo * lo + hi * hi; }
;             s[q] = a; }
; #pragma unroll
;         for (int o = 32; o > 0; o >>= 1) { s[0] += __shfl_xor(s[0], o); s[1] += __shfl_xor(s[1], o); }
; #pragma unroll
;         for (int q = 0; q < 2; ++q) { if (q == 1 && !two) break; const int rr = q ? r1 : r; const int cond = rr < MLAT ? (rr >> 13) : 8; const float* mp = modl + cond * 6144;
;             const float rstd = rsqrtf(s[q] * (1.0f / DM) + EPS);
.LBB0_586:
	v_ashrrev_i32_e32 v13, 31, v12
	v_lshlrev_b64 v[56:57], 11, v[12:13]
	s_waitcnt lgkmcnt(0)
	v_lshl_add_u64 v[10:11], v[2:3], 0, v[56:57]
	global_load_dwordx4 v[14:17], v[10:11], off
	global_load_dwordx4 v[28:31], v[10:11], off offset:1024
	v_min_i32_e32 v7, 0x10000, v12
	v_add_u32_e32 v10, s28, v12
	v_ashrrev_i32_e32 v7, 13, v7
	v_cmp_gt_i32_e32 vcc, s20, v10
	v_mul_i32_i24_e32 v18, 0x1800, v7
	v_ashrrev_i32_e32 v19, 31, v18
	v_cndmask_b32_e32 v12, v12, v10, vcc
	v_ashrrev_i32_e32 v13, 31, v12
	v_lshl_add_u64 v[18:19], v[18:19], 2, s[16:17]
	v_lshlrev_b64 v[12:13], 11, v[12:13]
	v_lshl_add_u64 v[58:59], v[18:19], 0, s[14:15]
	v_lshl_add_u64 v[12:13], v[2:3], 0, v[12:13]
	v_lshl_add_u64 v[40:41], v[58:59], 0, v[0:1]
	global_load_dwordx4 v[32:35], v[12:13], off
	global_load_dwordx4 v[80:83], v[40:41], off offset:2064
	global_load_dwordx4 v[84:87], v[40:41], off offset:2048
	global_load_dwordx4 v[36:39], v[40:41], off
	s_nop 0
	global_load_dwordx4 v[40:43], v[40:41], off offset:16
	s_nop 0
	global_load_dwordx4 v[44:47], v[12:13], off offset:1024
	v_lshl_add_u64 v[60:61], v[18:19], 0, v[0:1]
	global_load_dwordx4 v[88:91], v[60:61], off offset:2064
	global_load_dwordx4 v[92:95], v[60:61], off offset:2048
	global_load_dwordx4 v[48:51], v[60:61], off offset:16
	global_load_dwordx4 v[52:55], v[60:61], off
	v_min_i32_e32 v148, 0x10000, v10
	v_ashrrev_i32_e32 v148, 13, v148
	v_mul_i32_i24_e32 v148, 0x1800, v148
	v_ashrrev_i32_e32 v149, 31, v148
	v_lshl_add_u64 v[96:97], v[148:149], 2, s[16:17]
	v_lshl_add_u64 v[98:99], v[96:97], 0, s[14:15]
	v_lshl_add_u64 v[100:101], v[98:99], 0, v[0:1]
	global_load_dwordx4 v[102:105], v[100:101], off offset:2048
	global_load_dwordx4 v[106:109], v[100:101], off offset:2064
	global_load_dwordx4 v[110:113], v[100:101], off
	global_load_dwordx4 v[114:117], v[100:101], off offset:16
	v_lshl_add_u64 v[118:119], v[96:97], 0, v[0:1]
	global_load_dwordx4 v[120:123], v[118:119], off offset:2048
	global_load_dwordx4 v[124:127], v[118:119], off offset:2064
	global_load_dwordx4 v[128:131], v[118:119], off
	global_load_dwordx4 v[132:135], v[118:119], off offset:16
	s_waitcnt vmcnt(19)
	v_and_b32_e32 v11, 0xffff0000, v14
	v_and_b32_e32 v63, 0xffff0000, v15
	v_lshlrev_b32_e32 v7, 16, v14
	v_lshlrev_b32_e32 v62, 16, v15
	v_and_b32_e32 v67, 0xffff0000, v16
	v_mul_f32_e32 v27, v11, v11
	v_mul_f32_e32 v64, v63, v63
	v_lshlrev_b32_e32 v66, 16, v16
	v_and_b32_e32 v69, 0xffff0000, v17
	v_mul_f32_e32 v65, v67, v67
	v_fmac_f32_e32 v27, v7, v7
	v_fmac_f32_e32 v64, v62, v62
	v_lshlrev_b32_e32 v68, 16, v17
	s_waitcnt vmcnt(18)
	v_and_b32_e32 v17, 0xffff0000, v29
	v_and_b32_e32 v16, 0xffff0000, v28
	v_mul_f32_e32 v70, v69, v69
	v_fmac_f32_e32 v65, v66, v66
	v_add_f32_e32 v27, v27, v64
	v_lshlrev_b32_e32 v19, 16, v29
	v_lshlrev_b32_e32 v18, 16, v28
	v_pk_mul_f32 v[28:29], v[16:17], v[16:17]
	v_fmac_f32_e32 v70, v68, v68
	v_add_f32_e32 v27, v65, v27
	v_and_b32_e32 v13, 0xffff0000, v31
	v_and_b32_e32 v12, 0xffff0000, v30
	v_pk_fma_f32 v[28:29], v[18:19], v[18:19], v[28:29]
	v_add_f32_e32 v27, v70, v27
	v_lshlrev_b32_e32 v15, 16, v31
	v_lshlrev_b32_e32 v14, 16, v30
	v_pk_mul_f32 v[30:31], v[12:13], v[12:13]
	v_add_f32_e32 v27, v28, v27
	v_pk_fma_f32 v[30:31], v[14:15], v[14:15], v[30:31]
	v_add_f32_e32 v27, v29, v27
	v_add_f32_e32 v27, v30, v27
	v_add_f32_e32 v27, v31, v27
	ds_bpermute_b32 v28, v20, v27
	s_waitcnt vmcnt(14)
	v_add_f32_e32 v30, 1.0, v36
	v_add_f32_e32 v36, 1.0, v38
	s_waitcnt vmcnt(13)
	v_add_f32_e32 v38, 1.0, v40
	v_add_f32_e32 v40, 1.0, v43
	s_waitcnt lgkmcnt(0)
	v_add_f32_e32 v27, v27, v28
	ds_bpermute_b32 v28, v21, v27
	v_add_f32_e32 v31, 1.0, v37
	v_add_f32_e32 v37, 1.0, v39
	v_add_f32_e32 v39, 1.0, v42
	v_lshl_add_u64 v[64:65], v[4:5], 0, v[56:57]
	s_waitcnt lgkmcnt(0)
	v_add_f32_e32 v27, v27, v28
	ds_bpermute_b32 v28, v22, v27
	v_lshl_add_u64 v[56:57], v[58:59], 0, v[8:9]
	s_waitcnt lgkmcnt(0)
	v_add_f32_e32 v27, v27, v28
	ds_bpermute_b32 v28, v23, v27
	s_waitcnt lgkmcnt(0)
	v_add_f32_e32 v28, v27, v28
	ds_bpermute_b32 v29, v24, v28
	v_lshlrev_b32_e32 v27, 16, v32
	s_waitcnt lgkmcnt(0)
	v_add_f32_e32 v28, v28, v29
	ds_bpermute_b32 v29, v25, v28
	s_waitcnt lgkmcnt(0)
	v_add_f32_e32 v28, v28, v29
	v_fmamk_f32 v28, v28, 0x3a800000, v26
	v_mul_f32_e32 v29, 0x4b800000, v28
	v_cmp_gt_f32_e64 s[38:39], s21, v28
	s_nop 1
	v_cndmask_b32_e64 v28, v28, v29, s[38:39]
	v_rsq_f32_e32 v28, v28
	v_add_f32_e32 v29, 1.0, v41
	v_mul_f32_e32 v41, 0x45800000, v28
	v_cndmask_b32_e64 v43, v28, v41, s[38:39]
	v_mul_f32_e32 v7, v43, v7
	v_mul_f32_e32 v11, v43, v11
	v_mul_f32_e32 v28, v43, v62
	v_mul_f32_e32 v42, v43, v66
	v_mul_f32_e32 v41, v43, v63
	v_mul_f32_e32 v58, v43, v67
	v_mul_f32_e32 v59, v43, v68
	v_mul_f32_e32 v62, v43, v69
	s_waitcnt vmcnt(8)
; __device__ __forceinline__ unsigned cvt_pk_bf16(float lo, float hi) { unsigned r; asm volatile("v_cvt_pk_bf16_f32 %0, %1, %2" : "=v"(r) : "v"(lo), "v"(hi)); return r; }
; __device__ __forceinline__ float bflo(unsigned w) { return __uint_as_float(w << 16); }
; __device__ __forceinline__ float bfhi(unsigned w) { return __uint_as_float(w & 0xffff0000u); }
; __device__ __forceinline__ void norm_rows_b(const bf16_t* hb, int r_begin, int nrows, int stride, int second_off, const float* modl, int shoff, int scoff, bf16_t* xl) {
;     ...
;         for (int q = 0; q < 2; ++q) { float a = 0.f;
; #pragma unroll
;             for (int h = 0; h < 2; ++h)
; #pragma unroll
;                 for (int e = 0; e < 4; ++e) { const float lo = bflo(w[q][h][e]), hi = bfhi(w[q][h][e]); v[q][8 * h + 2 * e] = lo; v[q][8 * h + 2 * e + 1] = hi; a += lo * lo + hi * hi; }
;             s[q] = a; }
; #pragma unroll
;         for (int o = 32; o > 0; o >>= 1) { s[0] += __shfl_xor(s[0], o); s[1] += __shfl_xor(s[1], o); }
; #pragma unroll
;         for (int q = 0; q < 2; ++q) { if (q == 1 && !two) break; const int rr = q ? r1 : r; const int cond = rr < MLAT ? (rr >> 13) : 8; const float* mp = modl + cond * 6144;
;             const float rstd = rsqrtf(s[q] * (1.0f / DM) + EPS);
; #pragma unroll
;             for (int h = 0; h < 2; ++h) { const int col = 8 * lane + 512 * h; const f32x4 sc0 = *(const f32x4*)(mp + scoff + col), sc1 = *(const f32x4*)(mp + scoff + col + 4), sh0 = *(const f32x4*)(mp + shoff + col), sh1 = *(const f32x4*)(mp + shoff + col + 4);
;                 u32x4 o;
;                 o.x = cvt_pk_bf16(v[q][8 * h + 0] * rstd * (sc0[0] + 1.0f) + sh0[0], v[q][8 * h + 1] * rstd * (sc0[1] + 1.0f) + sh0[1]);
;                 o.y = cvt_pk_bf16(v[q][8 * h + 2] * rstd * (sc0[2] + 1.0f) + sh0[2], v[q][8 * h + 3] * rstd * (sc0[3] + 1.0f) + sh0[3]);
;                 o.z = cvt_pk_bf16(v[q][8 * h + 4] * rstd * (sc1[0] + 1.0f) + sh1[0], v[q][8 * h + 5] * rstd * (sc1[1] + 1.0f) + sh1[1]);
;                 o.w = cvt_pk_bf16(v[q][8 * h + 6] * rstd * (sc1[2] + 1.0f) + sh1[2], v[q][8 * h + 7] * rstd * (sc1[3] + 1.0f) + sh1[3]);
;                 *(u32x4*)(xl + (size_t)rr * DM + col) = o; } }
	v_fma_f32 v7, v30, v7, v52
	v_fma_f32 v11, v31, v11, v53
	v_fma_f32 v30, v36, v28, v54
	v_fma_f32 v31, v38, v42, v48
	v_fmac_f32_e32 v55, v37, v41
	v_fma_f32 v36, v29, v58, v49
	v_fma_f32 v37, v39, v59, v50
	v_fmac_f32_e32 v51, v40, v62
	v_cvt_pk_bf16_f32 v28, v7, v11
	v_cvt_pk_bf16_f32 v29, v30, v55
	v_cvt_pk_bf16_f32 v30, v31, v36
	v_cvt_pk_bf16_f32 v31, v37, v51
	global_store_dwordx4 v[64:65], v[28:31], off
	s_nop 0
	s_nop 0
	v_and_b32_e32 v28, 0xffff0000, v32
	v_and_b32_e32 v38, 0xffff0000, v33
	v_lshlrev_b32_e32 v37, 16, v33
	v_and_b32_e32 v40, 0xffff0000, v34
	v_mul_f32_e32 v7, v28, v28
	v_mul_f32_e32 v11, v38, v38
	v_lshlrev_b32_e32 v39, 16, v34
	v_lshlrev_b32_e32 v41, 16, v35
	v_and_b32_e32 v42, 0xffff0000, v35
	v_lshlrev_b32_e32 v36, 16, v44
	v_and_b32_e32 v35, 0xffff0000, v44
	v_mul_f32_e32 v44, v40, v40
	v_fmac_f32_e32 v7, v27, v27
	v_fmac_f32_e32 v11, v37, v37
	v_lshlrev_b32_e32 v34, 16, v45
	v_and_b32_e32 v33, 0xffff0000, v45
	v_mul_f32_e32 v45, v42, v42
	v_fmac_f32_e32 v44, v39, v39
	v_add_f32_e32 v7, v7, v11
	v_lshlrev_b32_e32 v32, 16, v46
	v_and_b32_e32 v31, 0xffff0000, v46
	v_mul_f32_e32 v46, v35, v35
	v_fmac_f32_e32 v45, v41, v41
	v_add_f32_e32 v7, v44, v7
	v_lshlrev_b32_e32 v30, 16, v47
	v_and_b32_e32 v29, 0xffff0000, v47
	v_mul_f32_e32 v47, v33, v33
	v_fmac_f32_e32 v46, v36, v36
	v_add_f32_e32 v7, v45, v7
	v_mul_f32_e32 v66, v31, v31
	v_fmac_f32_e32 v47, v34, v34
	v_add_f32_e32 v7, v46, v7
	v_mul_f32_e32 v67, v29, v29
	v_fmac_f32_e32 v66, v32, v32
	v_add_f32_e32 v7, v47, v7
	v_fmac_f32_e32 v67, v30, v30
	v_add_f32_e32 v7, v66, v7
	v_add_f32_e32 v7, v67, v7
	ds_bpermute_b32 v11, v20, v7
	v_mul_f32_e32 v14, v43, v14
	v_mul_f32_e32 v15, v43, v15
	v_mul_f32_e32 v18, v43, v18
	v_mul_f32_e32 v16, v43, v16
	s_waitcnt lgkmcnt(0)
	v_add_f32_e32 v7, v7, v11
	ds_bpermute_b32 v11, v21, v7
	v_mul_f32_e32 v19, v43, v19
	v_mul_f32_e32 v17, v43, v17
	v_mul_f32_e32 v12, v43, v12
	v_mul_f32_e32 v13, v43, v13
	s_waitcnt lgkmcnt(0)
	v_add_f32_e32 v7, v7, v11
	ds_bpermute_b32 v11, v22, v7
	s_waitcnt lgkmcnt(0)
	v_add_f32_e32 v7, v7, v11
	ds_bpermute_b32 v11, v23, v7
	s_waitcnt lgkmcnt(0)
	v_add_f32_e32 v7, v7, v11
	ds_bpermute_b32 v11, v24, v7
	s_waitcnt lgkmcnt(0)
	v_add_f32_e32 v7, v7, v11
	ds_bpermute_b32 v11, v25, v7
	s_waitcnt vmcnt(17)
	v_add_f32_e32 v47, 1.0, v80
	v_add_f32_e32 v48, 1.0, v81
	v_add_f32_e32 v49, 1.0, v82
	s_waitcnt vmcnt(16)
	v_add_f32_e32 v43, 1.0, v84
	v_add_f32_e32 v44, 1.0, v85
	v_add_f32_e32 v45, 1.0, v86
	v_add_f32_e32 v46, 1.0, v87
	v_add_f32_e32 v50, 1.0, v83
	s_waitcnt vmcnt(12)
	v_fma_f32 v14, v14, v47, v88
	v_fma_f32 v15, v15, v49, v90
	s_waitcnt vmcnt(11)
	v_fma_f32 v18, v43, v18, v92
	v_fma_f32 v16, v44, v16, v93
	v_fma_f32 v19, v45, v19, v94
	v_fma_f32 v63, v46, v17, v95
	v_fma_f32 v17, v12, v48, v89
	v_fma_f32 v59, v13, v50, v91
	v_cvt_pk_bf16_f32 v12, v18, v16
	v_cvt_pk_bf16_f32 v13, v19, v63
	v_cvt_pk_bf16_f32 v14, v14, v17
	v_cvt_pk_bf16_f32 v15, v15, v59
	global_store_dwordx4 v[64:65], v[12:15], off offset:1024
	s_and_saveexec_b64 s[18:19], vcc
	s_cbranch_execz .LBB0_585
	s_waitcnt lgkmcnt(0)
	v_add_f32_e32 v43, v7, v11
	v_fmamk_f32 v43, v43, 0x3a800000, v26
	v_mul_f32_e32 v56, 0x4b800000, v43
	v_cmp_gt_f32_e32 vcc, s21, v43
	v_mov_b32_e32 v7, v1
	v_lshl_add_u64 v[52:53], v[98:99], 0, v[6:7]
	v_cndmask_b32_e32 v43, v43, v56, vcc
	v_rsq_f32_e32 v43, v43
	v_ashrrev_i32_e32 v11, 31, v10
	v_lshlrev_b64 v[56:57], 11, v[10:11]
	v_lshl_add_u64 v[56:57], v[4:5], 0, v[56:57]
	v_mul_f32_e32 v7, 0x45800000, v43
	v_cndmask_b32_e32 v7, v43, v7, vcc
	v_mul_f32_e32 v11, v7, v27
	v_mul_f32_e32 v27, v7, v28
	v_mul_f32_e32 v28, v7, v37
	v_mul_f32_e32 v37, v7, v38
	v_mul_f32_e32 v38, v7, v39
	v_mul_f32_e32 v39, v7, v40
	v_mul_f32_e32 v40, v7, v41
	v_mul_f32_e32 v41, v7, v42
	v_mul_f32_e32 v33, v7, v33
	v_mul_f32_e32 v32, v7, v32
	v_mul_f32_e32 v31, v7, v31
	v_mul_f32_e32 v30, v7, v30
	s_waitcnt vmcnt(7)
	v_add_f32_e32 v12, 1.0, v110
	v_add_f32_e32 v13, 1.0, v111
	v_add_f32_e32 v14, 1.0, v112
	v_add_f32_e32 v15, 1.0, v113
	s_waitcnt vmcnt(6)
	v_add_f32_e32 v16, 1.0, v114
	v_add_f32_e32 v17, 1.0, v115
	v_add_f32_e32 v18, 1.0, v116
	v_add_f32_e32 v19, 1.0, v117
	s_waitcnt vmcnt(3)
	v_fma_f32 v11, v11, v12, v128
	v_fma_f32 v12, v27, v13, v129
	v_fma_f32 v13, v28, v14, v130
	v_fma_f32 v47, v37, v15, v131
	s_waitcnt vmcnt(2)
	v_fma_f32 v14, v38, v16, v132
	v_fma_f32 v15, v39, v17, v133
	v_fma_f32 v16, v40, v18, v134
	v_fma_f32 v51, v41, v19, v135
	v_cvt_pk_bf16_f32 v12, v11, v12
	v_cvt_pk_bf16_f32 v13, v13, v47
	v_cvt_pk_bf16_f32 v14, v14, v15
	v_cvt_pk_bf16_f32 v15, v16, v51
	global_store_dwordx4 v[56:57], v[12:15], off
	s_nop 0
	v_mul_f32_e32 v11, v7, v36
	v_mul_f32_e32 v27, v7, v35
	v_mul_f32_e32 v28, v7, v34
	v_mul_f32_e32 v7, v7, v29
	s_waitcnt vmcnt(10)
	v_add_f32_e32 v12, 1.0, v102
	v_add_f32_e32 v13, 1.0, v103
	v_add_f32_e32 v14, 1.0, v104
	v_add_f32_e32 v15, 1.0, v105
	s_waitcnt vmcnt(9)
	v_add_f32_e32 v16, 1.0, v106
	v_add_f32_e32 v17, 1.0, v107
	v_add_f32_e32 v18, 1.0, v108
	v_add_f32_e32 v19, 1.0, v109
	s_waitcnt vmcnt(6)
	v_fma_f32 v11, v11, v12, v120
	v_fma_f32 v12, v27, v13, v121
	v_fma_f32 v13, v28, v14, v122
	v_fma_f32 v41, v33, v15, v123
	s_waitcnt vmcnt(5)
	v_fma_f32 v14, v32, v16, v124
	v_fma_f32 v15, v31, v17, v125
	v_fma_f32 v16, v30, v18, v126
	v_fma_f32 v45, v7, v19, v127
	v_cvt_pk_bf16_f32 v12, v11, v12
	v_cvt_pk_bf16_f32 v13, v13, v41
	v_cvt_pk_bf16_f32 v14, v14, v15
	v_cvt_pk_bf16_f32 v15, v16, v45
	global_store_dwordx4 v[56:57], v[12:15], off offset:1024
	s_branch .LBB0_585

; __device__ __forceinline__ float bflo(unsigned w) { return __uint_as_float(w << 16); }
; __device__ __forceinline__ float bfhi(unsigned w) { return __uint_as_float(w & 0xffff0000u); }
; __device__ __forceinline__ void norm_rows_b(const bf16_t* hb, int r_begin, int nrows, int stride, int second_off, const float* modl, int shoff, int scoff, bf16_t* xl) {
;     ...
;     for (int r = r_begin; r < nrows; r += stride) {
;         const int r1 = r + second_off; const bool two = r1 < nrows;
;         u32x4 w[2][2]; float s[2];
; #pragma unroll
;         for (int q = 0; q < 2; ++q) { const bf16_t* xr = hb + (size_t)(q ? (two ? r1 : r) : r) * DM + 8 * lane; w[q][0] = *(const u32x4*)(xr); w[q][1] = *(const u32x4*)(xr + 512); }
;         float v[2][16];
; #pragma unroll
;         for (int q = 0; q < 2; ++q) { float a = 0.f;
; #pragma unroll
;             for (int h = 0; h < 2; ++h)
; #pragma unroll
;                 for (int e = 0; e < 4; ++e) { const float lo = bflo(w[q][h][e]), hi = bfhi(w[q][h][e]); v[q][8 * h + 2 * e] = lo; v[q][8 * h + 2 * e + 1] = hi; a += lo * lo + hi * hi; }
;             s[q] = a; }
; #pragma unroll
;         for (int o = 32; o > 0; o >>= 1) { s[0] += __shfl_xor(s[0], o); s[1] += __shfl_xor(s[1], o); }
; #pragma unroll
;         for (int q = 0; q < 2; ++q) { if (q == 1 && !two) break; const int rr = q ? r1 : r; const int cond = rr < MLAT ? (rr >> 13) : 8; const float* mp = modl + cond * 6144;
;             const float rstd = rsqrtf(s[q] * (1.0f / DM) + EPS);
.LBB0_984:
	v_ashrrev_i32_e32 v13, 31, v12
	v_lshlrev_b64 v[50:51], 11, v[12:13]
	s_waitcnt lgkmcnt(0)
	v_lshl_add_u64 v[10:11], v[2:3], 0, v[50:51]
	global_load_dwordx4 v[18:21], v[10:11], off
	global_load_dwordx4 v[22:25], v[10:11], off offset:1024
	v_add_u32_e32 v10, s34, v12
	v_ashrrev_i32_e32 v7, 13, v12
	v_cmp_gt_i32_e32 vcc, s22, v10
	v_mul_i32_i24_e32 v14, 0x1800, v7
	v_ashrrev_i32_e32 v15, 31, v14
	v_cndmask_b32_e32 v12, v12, v10, vcc
	v_ashrrev_i32_e32 v13, 31, v12
	v_lshl_add_u64 v[14:15], v[14:15], 2, s[16:17]
	v_lshlrev_b64 v[12:13], 11, v[12:13]
	v_lshl_add_u64 v[52:53], v[14:15], 0, s[18:19]
	v_lshl_add_u64 v[12:13], v[2:3], 0, v[12:13]
	v_lshl_add_u64 v[34:35], v[52:53], 0, v[0:1]
	global_load_dwordx4 v[30:33], v[12:13], off
	global_load_dwordx4 v[80:83], v[34:35], off offset:2064
	global_load_dwordx4 v[84:87], v[34:35], off offset:2048
	global_load_dwordx4 v[26:29], v[34:35], off
	s_nop 0
	global_load_dwordx4 v[34:37], v[34:35], off offset:16
	v_lshl_add_u64 v[54:55], v[14:15], 0, s[20:21]
	global_load_dwordx4 v[38:41], v[12:13], off offset:1024
	v_lshl_add_u64 v[12:13], v[54:55], 0, v[0:1]
	global_load_dwordx4 v[88:91], v[12:13], off offset:2064
	global_load_dwordx4 v[92:95], v[12:13], off offset:2048
	global_load_dwordx4 v[42:45], v[12:13], off offset:16
	global_load_dwordx4 v[46:49], v[12:13], off
	v_lshl_add_u64 v[60:61], v[4:5], 0, v[50:51]
	v_lshl_add_u64 v[50:51], v[54:55], 0, v[8:9]
	v_ashrrev_i32_e32 v148, 13, v10
	v_mul_i32_i24_e32 v148, 0x1800, v148
	v_ashrrev_i32_e32 v149, 31, v148
	v_lshl_add_u64 v[96:97], v[148:149], 2, s[16:17]
	v_lshl_add_u64 v[98:99], v[96:97], 0, s[18:19]
	v_lshl_add_u64 v[100:101], v[98:99], 0, v[0:1]
	v_lshl_add_u64 v[102:103], v[96:97], 0, s[20:21]
	global_load_dwordx4 v[104:107], v[100:101], off offset:2048
	global_load_dwordx4 v[108:111], v[100:101], off offset:2064
	global_load_dwordx4 v[112:115], v[100:101], off
	global_load_dwordx4 v[116:119], v[100:101], off offset:16
	v_lshl_add_u64 v[120:121], v[102:103], 0, v[0:1]
	global_load_dwordx4 v[122:125], v[120:121], off offset:2048
	global_load_dwordx4 v[126:129], v[120:121], off offset:2064
	global_load_dwordx4 v[130:133], v[120:121], off
	global_load_dwordx4 v[134:137], v[120:121], off offset:16
	s_waitcnt vmcnt(19)
	v_and_b32_e32 v11, 0xffff0000, v18
	v_and_b32_e32 v63, 0xffff0000, v19
	v_lshlrev_b32_e32 v7, 16, v18
	v_lshlrev_b32_e32 v62, 16, v19
	v_and_b32_e32 v65, 0xffff0000, v20
	s_waitcnt vmcnt(18)
	v_lshlrev_b32_e32 v56, 16, v22
	v_and_b32_e32 v58, 0xffff0000, v22
	v_mul_f32_e32 v17, v11, v11
	v_mul_f32_e32 v22, v63, v63
	v_lshlrev_b32_e32 v64, 16, v20
	v_and_b32_e32 v67, 0xffff0000, v21
	v_lshlrev_b32_e32 v57, 16, v23
	v_and_b32_e32 v59, 0xffff0000, v23
	v_mul_f32_e32 v23, v65, v65
	v_fmac_f32_e32 v17, v7, v7
	v_fmac_f32_e32 v22, v62, v62
	v_lshlrev_b32_e32 v66, 16, v21
	v_lshlrev_b32_e32 v14, 16, v24
	v_and_b32_e32 v12, 0xffff0000, v24
	v_mul_f32_e32 v24, v67, v67
	v_fmac_f32_e32 v23, v64, v64
	v_add_f32_e32 v17, v17, v22
	v_pk_mul_f32 v[18:19], v[58:59], v[58:59]
	v_fmac_f32_e32 v24, v66, v66
	v_add_f32_e32 v17, v23, v17
	v_and_b32_e32 v13, 0xffff0000, v25
	v_pk_fma_f32 v[18:19], v[56:57], v[56:57], v[18:19]
	v_add_f32_e32 v17, v24, v17
	v_lshlrev_b32_e32 v15, 16, v25
	v_pk_mul_f32 v[20:21], v[12:13], v[12:13]
	v_add_f32_e32 v17, v18, v17
	v_pk_fma_f32 v[20:21], v[14:15], v[14:15], v[20:21]
	v_add_f32_e32 v17, v19, v17
	v_add_f32_e32 v17, v20, v17
	v_add_f32_e32 v17, v21, v17
	ds_bpermute_b32 v18, v205, v17
	s_waitcnt vmcnt(14)
	v_add_f32_e32 v25, 1.0, v29
	v_add_f32_e32 v20, 1.0, v26
	v_add_f32_e32 v21, 1.0, v27
	v_add_f32_e32 v24, 1.0, v28
	s_waitcnt lgkmcnt(0)
	v_add_f32_e32 v17, v17, v18
	ds_bpermute_b32 v18, v206, v17
	s_waitcnt vmcnt(13)
	v_add_f32_e32 v26, 1.0, v34
	v_add_f32_e32 v27, 1.0, v36
	v_add_f32_e32 v28, 1.0, v37
	v_lshl_add_u64 v[22:23], v[52:53], 0, v[8:9]
	s_waitcnt lgkmcnt(0)
	v_add_f32_e32 v17, v17, v18
	ds_bpermute_b32 v18, v207, v17
	s_waitcnt lgkmcnt(0)
	v_add_f32_e32 v17, v17, v18
	ds_bpermute_b32 v18, v208, v17
	s_waitcnt lgkmcnt(0)
	v_add_f32_e32 v18, v17, v18
	ds_bpermute_b32 v19, v209, v18
	v_lshlrev_b32_e32 v17, 16, v30
	s_waitcnt lgkmcnt(0)
	v_add_f32_e32 v18, v18, v19
	ds_bpermute_b32 v19, v210, v18
	s_waitcnt lgkmcnt(0)
	v_add_f32_e32 v18, v18, v19
	v_fmamk_f32 v18, v18, 0x3a800000, v16
	v_mul_f32_e32 v19, 0x4b800000, v18
	v_cmp_gt_f32_e64 s[2:3], s23, v18
	s_nop 1
	v_cndmask_b32_e64 v18, v18, v19, s[2:3]
	v_rsq_f32_e32 v18, v18
	v_add_f32_e32 v19, 1.0, v35
	v_mul_f32_e32 v29, 0x45800000, v18
	v_cndmask_b32_e64 v54, v18, v29, s[2:3]
	v_mul_f32_e32 v7, v54, v7
	v_mul_f32_e32 v11, v54, v11
	v_mul_f32_e32 v18, v54, v62
	v_mul_f32_e32 v34, v54, v64
	v_mul_f32_e32 v29, v54, v63
	v_mul_f32_e32 v35, v54, v65
	v_mul_f32_e32 v36, v54, v66
	v_mul_f32_e32 v37, v54, v67
	s_waitcnt vmcnt(8)
; __device__ __forceinline__ unsigned cvt_pk_bf16(float lo, float hi) { unsigned r; asm volatile("v_cvt_pk_bf16_f32 %0, %1, %2" : "=v"(r) : "v"(lo), "v"(hi)); return r; }
; __device__ __forceinline__ float bflo(unsigned w) { return __uint_as_float(w << 16); }
; __device__ __forceinline__ float bfhi(unsigned w) { return __uint_as_float(w & 0xffff0000u); }
; __device__ __forceinline__ void norm_rows_b(const bf16_t* hb, int r_begin, int nrows, int stride, int second_off, const float* modl, int shoff, int scoff, bf16_t* xl) {
;     ...
;         for (int q = 0; q < 2; ++q) { float a = 0.f;
; #pragma unroll
;             for (int h = 0; h < 2; ++h)
; #pragma unroll
;                 for (int e = 0; e < 4; ++e) { const float lo = bflo(w[q][h][e]), hi = bfhi(w[q][h][e]); v[q][8 * h + 2 * e] = lo; v[q][8 * h + 2 * e + 1] = hi; a += lo * lo + hi * hi; }
;             s[q] = a; }
; #pragma unroll
;         for (int o = 32; o > 0; o >>= 1) { s[0] += __shfl_xor(s[0], o); s[1] += __shfl_xor(s[1], o); }
; #pragma unroll
;         for (int q = 0; q < 2; ++q) { if (q == 1 && !two) break; const int rr = q ? r1 : r; const int cond = rr < MLAT ? (rr >> 13) : 8; const float* mp = modl + cond * 6144;
;             const float rstd = rsqrtf(s[q] * (1.0f / DM) + EPS);
; #pragma unroll
;             for (int h = 0; h < 2; ++h) { const int col = 8 * lane + 512 * h; const f32x4 sc0 = *(const f32x4*)(mp + scoff + col), sc1 = *(const f32x4*)(mp + scoff + col + 4), sh0 = *(const f32x4*)(mp + shoff + col), sh1 = *(const f32x4*)(mp + shoff + col + 4);
;                 u32x4 o;
;                 o.x = cvt_pk_bf16(v[q][8 * h + 0] * rstd * (sc0[0] + 1.0f) + sh0[0], v[q][8 * h + 1] * rstd * (sc0[1] + 1.0f) + sh0[1]);
;                 o.y = cvt_pk_bf16(v[q][8 * h + 2] * rstd * (sc0[2] + 1.0f) + sh0[2], v[q][8 * h + 3] * rstd * (sc0[3] + 1.0f) + sh0[3]);
;                 o.z = cvt_pk_bf16(v[q][8 * h + 4] * rstd * (sc1[0] + 1.0f) + sh1[0], v[q][8 * h + 5] * rstd * (sc1[1] + 1.0f) + sh1[1]);
;                 o.w = cvt_pk_bf16(v[q][8 * h + 6] * rstd * (sc1[2] + 1.0f) + sh1[2], v[q][8 * h + 7] * rstd * (sc1[3] + 1.0f) + sh1[3]);
;                 *(u32x4*)(xl + (size_t)rr * DM + col) = o; } }
	v_fma_f32 v7, v20, v7, v46
	v_fma_f32 v11, v21, v11, v47
	v_fma_f32 v20, v24, v18, v48
	v_fma_f32 v21, v26, v34, v42
	v_fmac_f32_e32 v49, v25, v29
	v_fma_f32 v24, v19, v35, v43
	v_fma_f32 v25, v27, v36, v44
	v_fmac_f32_e32 v45, v28, v37
	v_cvt_pk_bf16_f32 v18, v7, v11
	v_cvt_pk_bf16_f32 v19, v20, v49
	v_cvt_pk_bf16_f32 v20, v21, v24
	v_cvt_pk_bf16_f32 v21, v25, v45
	global_store_dwordx4 v[60:61], v[18:21], off
	s_nop 0
	v_and_b32_e32 v24, 0xffff0000, v30
	v_and_b32_e32 v28, 0xffff0000, v31
	v_lshlrev_b32_e32 v27, 16, v31
	v_and_b32_e32 v30, 0xffff0000, v32
	v_mul_f32_e32 v7, v24, v24
	v_mul_f32_e32 v11, v28, v28
	v_lshlrev_b32_e32 v29, 16, v32
	v_lshlrev_b32_e32 v31, 16, v33
	v_and_b32_e32 v32, 0xffff0000, v33
	v_mul_f32_e32 v33, v30, v30
	v_fmac_f32_e32 v7, v17, v17
	v_fmac_f32_e32 v11, v27, v27
	v_lshlrev_b32_e32 v26, 16, v38
	v_and_b32_e32 v25, 0xffff0000, v38
	v_mul_f32_e32 v38, v32, v32
	v_fmac_f32_e32 v33, v29, v29
	v_add_f32_e32 v7, v7, v11
	v_lshlrev_b32_e32 v23, 16, v39
	v_and_b32_e32 v22, 0xffff0000, v39
	v_mul_f32_e32 v39, v25, v25
	v_fmac_f32_e32 v38, v31, v31
	v_add_f32_e32 v7, v33, v7
	v_lshlrev_b32_e32 v21, 16, v40
	v_and_b32_e32 v20, 0xffff0000, v40
	v_mul_f32_e32 v40, v22, v22
	v_fmac_f32_e32 v39, v26, v26
	v_add_f32_e32 v7, v38, v7
	v_lshlrev_b32_e32 v19, 16, v41
	v_and_b32_e32 v18, 0xffff0000, v41
	v_mul_f32_e32 v41, v20, v20
	v_fmac_f32_e32 v40, v23, v23
	v_add_f32_e32 v7, v39, v7
	v_mul_f32_e32 v55, v18, v18
	v_fmac_f32_e32 v41, v21, v21
	v_add_f32_e32 v7, v40, v7
	v_fmac_f32_e32 v55, v19, v19
	v_add_f32_e32 v7, v41, v7
	v_add_f32_e32 v7, v55, v7
	ds_bpermute_b32 v11, v205, v7
	v_mul_f32_e32 v14, v54, v14
	v_mul_f32_e32 v15, v54, v15
	v_mul_f32_e32 v33, v54, v56
	v_mul_f32_e32 v38, v54, v58
	s_waitcnt lgkmcnt(0)
	v_add_f32_e32 v7, v7, v11
	ds_bpermute_b32 v11, v206, v7
	v_mul_f32_e32 v39, v54, v57
	v_mul_f32_e32 v40, v54, v59
	v_mul_f32_e32 v12, v54, v12
	v_mul_f32_e32 v13, v54, v13
	s_waitcnt lgkmcnt(0)
	v_add_f32_e32 v7, v7, v11
	ds_bpermute_b32 v11, v207, v7
	s_waitcnt lgkmcnt(0)
	v_add_f32_e32 v7, v7, v11
	ds_bpermute_b32 v11, v208, v7
	s_waitcnt lgkmcnt(0)
	v_add_f32_e32 v7, v7, v11
	ds_bpermute_b32 v11, v209, v7
	s_waitcnt lgkmcnt(0)
	v_add_f32_e32 v7, v7, v11
	ds_bpermute_b32 v11, v210, v7
	s_waitcnt vmcnt(17)
	v_add_f32_e32 v34, 1.0, v80
	v_add_f32_e32 v36, 1.0, v82
	s_waitcnt vmcnt(16)
	v_add_f32_e32 v41, 1.0, v84
	v_add_f32_e32 v42, 1.0, v85
	v_add_f32_e32 v43, 1.0, v86
	v_add_f32_e32 v44, 1.0, v87
	v_add_f32_e32 v35, 1.0, v81
	v_add_f32_e32 v37, 1.0, v83
	s_waitcnt vmcnt(12)
	v_fma_f32 v14, v14, v34, v88
	v_fma_f32 v15, v15, v36, v90
	s_waitcnt vmcnt(11)
	v_fma_f32 v33, v41, v33, v92
	v_fma_f32 v38, v42, v38, v93
	v_fma_f32 v39, v43, v39, v94
	v_fma_f32 v53, v44, v40, v95
	v_fma_f32 v34, v12, v35, v89
	v_fma_f32 v49, v13, v37, v91
	v_cvt_pk_bf16_f32 v12, v33, v38
	v_cvt_pk_bf16_f32 v13, v39, v53
	v_cvt_pk_bf16_f32 v14, v14, v34
	v_cvt_pk_bf16_f32 v15, v15, v49
	global_store_dwordx4 v[60:61], v[12:15], off offset:1024
	s_and_saveexec_b64 s[2:3], vcc
	s_cbranch_execz .LBB0_983
	s_waitcnt lgkmcnt(0)
	v_add_f32_e32 v33, v7, v11
	v_fmamk_f32 v33, v33, 0x3a800000, v16
	v_mul_f32_e32 v50, 0x4b800000, v33
	v_cmp_gt_f32_e32 vcc, s23, v33
	v_ashrrev_i32_e32 v11, 31, v10
	v_mov_b32_e32 v7, v1
	v_cndmask_b32_e32 v33, v33, v50, vcc
	v_rsq_f32_e32 v33, v33
	v_lshlrev_b64 v[50:51], 11, v[10:11]
	v_lshl_add_u64 v[50:51], v[4:5], 0, v[50:51]
	v_lshl_add_u64 v[46:47], v[98:99], 0, v[6:7]
	v_mul_f32_e32 v11, 0x45800000, v33
	v_cndmask_b32_e32 v11, v33, v11, vcc
	v_mul_f32_e32 v17, v11, v17
	v_mul_f32_e32 v24, v11, v24
	v_mul_f32_e32 v27, v11, v27
	v_mul_f32_e32 v28, v11, v28
	v_mul_f32_e32 v29, v11, v29
	v_mul_f32_e32 v30, v11, v30
	v_mul_f32_e32 v31, v11, v31
	v_mul_f32_e32 v32, v11, v32
	v_mul_f32_e32 v23, v11, v23
	v_mul_f32_e32 v22, v11, v22
	v_mul_f32_e32 v21, v11, v21
	v_mul_f32_e32 v20, v11, v20
	v_mul_f32_e32 v19, v11, v19
	s_waitcnt vmcnt(7)
	v_add_f32_e32 v12, 1.0, v112
	v_add_f32_e32 v13, 1.0, v113
	v_add_f32_e32 v14, 1.0, v114
	v_add_f32_e32 v15, 1.0, v115
	s_waitcnt vmcnt(6)
	v_add_f32_e32 v33, 1.0, v116
	v_add_f32_e32 v34, 1.0, v117
	v_add_f32_e32 v35, 1.0, v118
	v_add_f32_e32 v36, 1.0, v119
	s_waitcnt vmcnt(3)
	v_fma_f32 v12, v17, v12, v130
	v_fma_f32 v13, v24, v13, v131
	v_fma_f32 v14, v27, v14, v132
	v_fma_f32 v41, v28, v15, v133
	s_waitcnt vmcnt(2)
	v_fma_f32 v15, v29, v33, v134
	v_fma_f32 v17, v30, v34, v135
	v_fma_f32 v24, v31, v35, v136
	v_fma_f32 v45, v32, v36, v137
	v_cvt_pk_bf16_f32 v12, v12, v13
	v_cvt_pk_bf16_f32 v13, v14, v41
	v_cvt_pk_bf16_f32 v14, v15, v17
	v_cvt_pk_bf16_f32 v15, v24, v45
	global_store_dwordx4 v[50:51], v[12:15], off
	s_nop 0
	v_lshl_add_u64 v[36:37], v[102:103], 0, v[6:7]
	s_nop 0
	v_mul_f32_e32 v7, v11, v26
	v_mul_f32_e32 v17, v11, v25
	v_mul_f32_e32 v11, v11, v18
	s_waitcnt vmcnt(10)
	v_add_f32_e32 v12, 1.0, v104
	v_add_f32_e32 v13, 1.0, v105
	v_add_f32_e32 v14, 1.0, v106
	v_add_f32_e32 v15, 1.0, v107
	s_waitcnt vmcnt(9)
	v_add_f32_e32 v18, 1.0, v108
	v_add_f32_e32 v24, 1.0, v109
	v_add_f32_e32 v25, 1.0, v110
	v_add_f32_e32 v26, 1.0, v111
	s_waitcnt vmcnt(6)
	v_fma_f32 v7, v7, v12, v122
	v_fma_f32 v12, v17, v13, v123
	v_fma_f32 v13, v23, v14, v124
	v_fma_f32 v35, v22, v15, v125
	s_waitcnt vmcnt(5)
	v_fma_f32 v14, v21, v18, v126
	v_fma_f32 v15, v20, v24, v127
	v_fma_f32 v17, v19, v25, v128
	v_fma_f32 v39, v11, v26, v129
	v_cvt_pk_bf16_f32 v12, v7, v12
	v_cvt_pk_bf16_f32 v13, v13, v35
	v_cvt_pk_bf16_f32 v14, v14, v15
	v_cvt_pk_bf16_f32 v15, v17, v39
	global_store_dwordx4 v[50:51], v[12:15], off offset:1024
	s_branch .LBB0_983
